# FFN1 K-loop: 4 of the 6 LDS-DMA loads of the heavy phases issued between MFMAs instead of in the load section (counted waits adjusted)
# speedup vs baseline: 1.0013x; 1.0013x over previous
.LBB0_1916:
	s_add_u32 s2, s54, 0xfffc0080
	s_addc_u32 s3, s55, -1
	s_add_i32 vcc_lo, 0, 0x10000
	s_cmp_eq_u32 s81, 12
	s_cselect_b32 s3, s0, s3
	s_cselect_b32 s2, s1, s2
	v_add_u32_e32 v136, vcc_lo, v140
	s_cselect_b32 s83, s23, s80
	s_cselect_b32 s82, s25, s49
	s_add_i32 vcc_hi, 0, 0x14000
	ds_read_b128 v[132:135], v136
	ds_read_b128 v[144:147], v136 offset:1024
	ds_read_b128 v[148:151], v136 offset:2048
	ds_read_b128 v[152:155], v136 offset:3072
	v_add_u32_e32 v136, vcc_hi, v140
	ds_read_b128 v[156:159], v136
	ds_read_b128 v[160:163], v136 offset:1024
	ds_read_b128 v[164:167], v136 offset:2048
	ds_read_b128 v[168:171], v136 offset:3072
	v_lshl_add_u64 v[136:137], s[54:55], 0, v[130:131]
	s_add_i32 m0, s51, 0xc000
	ds_read_b128 v[172:175], v142
	ds_read_b128 v[176:179], v142 offset:1024
	ds_read_b128 v[180:183], v142 offset:2048
	ds_read_b128 v[200:203], v142 offset:3072
	ds_read_b128 v[204:207], v142 offset:4096
	ds_read_b128 v[208:211], v142 offset:5120
	ds_read_b128 v[212:215], v142 offset:6144
	ds_read_b128 v[216:219], v142 offset:7168
	global_load_lds_dwordx4 v[136:137], off
	v_lshl_add_u64 v[136:137], v[136:137], 0, s[84:85]
	s_add_i32 m0, s51, 0xe000
	s_nop 0
	global_load_lds_dwordx4 v[136:137], off
	s_waitcnt vmcnt(8)
	s_waitcnt lgkmcnt(0)
	s_barrier
	s_waitcnt lgkmcnt(0)
	v_mfma_f32_16x16x32_bf16 v[124:127], v[132:135], v[172:175], v[124:127]
	v_mfma_f32_16x16x32_bf16 v[120:123], v[148:151], v[172:175], v[120:123]
	v_mfma_f32_16x16x32_bf16 v[108:111], v[132:135], v[180:183], v[108:111]
	v_mfma_f32_16x16x32_bf16 v[104:107], v[148:151], v[180:183], v[104:107]
	v_mfma_f32_16x16x32_bf16 v[92:95], v[132:135], v[204:207], v[92:95]
	v_mfma_f32_16x16x32_bf16 v[88:91], v[148:151], v[204:207], v[88:91]
	v_mfma_f32_16x16x32_bf16 v[76:79], v[132:135], v[212:215], v[76:79]
	v_mfma_f32_16x16x32_bf16 v[72:75], v[148:151], v[212:215], v[72:75]
	v_mfma_f32_16x16x32_bf16 v[124:127], v[144:147], v[176:179], v[124:127]
	v_mfma_f32_16x16x32_bf16 v[120:123], v[152:155], v[176:179], v[120:123]
	v_mfma_f32_16x16x32_bf16 v[108:111], v[144:147], v[200:203], v[108:111]
	v_mfma_f32_16x16x32_bf16 v[104:107], v[152:155], v[200:203], v[104:107]
	v_mfma_f32_16x16x32_bf16 v[92:95], v[144:147], v[208:211], v[92:95]
	v_mfma_f32_16x16x32_bf16 v[88:91], v[152:155], v[208:211], v[88:91]
	v_mfma_f32_16x16x32_bf16 v[76:79], v[144:147], v[216:219], v[76:79]
	v_mfma_f32_16x16x32_bf16 v[72:75], v[152:155], v[216:219], v[72:75]
	v_mfma_f32_16x16x32_bf16 v[116:119], v[156:159], v[172:175], v[116:119]
	v_mfma_f32_16x16x32_bf16 v[112:115], v[164:167], v[172:175], v[112:115]
	v_mfma_f32_16x16x32_bf16 v[100:103], v[156:159], v[180:183], v[100:103]
	v_mfma_f32_16x16x32_bf16 v[96:99], v[164:167], v[180:183], v[96:99]
	v_mfma_f32_16x16x32_bf16 v[84:87], v[156:159], v[204:207], v[84:87]
	v_mfma_f32_16x16x32_bf16 v[80:83], v[164:167], v[204:207], v[80:83]
	v_mfma_f32_16x16x32_bf16 v[68:71], v[156:159], v[212:215], v[68:71]
	v_mfma_f32_16x16x32_bf16 v[64:67], v[164:167], v[212:215], v[64:67]
	v_mfma_f32_16x16x32_bf16 v[116:119], v[160:163], v[176:179], v[116:119]
	v_mfma_f32_16x16x32_bf16 v[112:115], v[168:171], v[176:179], v[112:115]
	v_mfma_f32_16x16x32_bf16 v[100:103], v[160:163], v[200:203], v[100:103]
	v_mfma_f32_16x16x32_bf16 v[96:99], v[168:171], v[200:203], v[96:99]
	v_mfma_f32_16x16x32_bf16 v[84:87], v[160:163], v[208:211], v[84:87]
	v_mfma_f32_16x16x32_bf16 v[80:83], v[168:171], v[208:211], v[80:83]
	v_mfma_f32_16x16x32_bf16 v[68:71], v[160:163], v[216:219], v[68:71]
	v_mfma_f32_16x16x32_bf16 v[64:67], v[168:171], v[216:219], v[64:67]
	s_barrier
	v_lshl_add_u64 v[136:137], s[82:83], 0, v[184:185]
	s_add_i32 s82, vcc_lo, s50
	s_mov_b32 m0, s82
	ds_read_b128 v[172:175], v142 offset:16384
	ds_read_b128 v[176:179], v142 offset:17408
	ds_read_b128 v[180:183], v142 offset:18432
	ds_read_b128 v[200:203], v142 offset:19456
	ds_read_b128 v[204:207], v142 offset:20480
	ds_read_b128 v[208:211], v142 offset:21504
	ds_read_b128 v[212:215], v142 offset:22528
	ds_read_b128 v[216:219], v142 offset:23552
	global_load_lds_dwordx4 v[136:137], off
	v_lshl_add_u64 v[220:221], v[136:137], 0, s[84:85]
	s_add_i32 m0, s82, 0x2000
	s_add_i32 s82, vcc_hi, s50
	global_load_lds_dwordx4 v[220:221], off
	s_waitcnt vmcnt(4)
	s_waitcnt lgkmcnt(0)
	s_barrier
	s_waitcnt lgkmcnt(0)
	v_mfma_f32_16x16x32_bf16 v[60:63], v[132:135], v[172:175], v[60:63]
	v_mfma_f32_16x16x32_bf16 v[56:59], v[148:151], v[172:175], v[56:59]
	v_mfma_f32_16x16x32_bf16 v[44:47], v[132:135], v[180:183], v[44:47]
	v_mfma_f32_16x16x32_bf16 v[40:43], v[148:151], v[180:183], v[40:43]
	v_mfma_f32_16x16x32_bf16 v[28:31], v[132:135], v[204:207], v[28:31]
	v_mfma_f32_16x16x32_bf16 v[24:27], v[148:151], v[204:207], v[24:27]
	v_mfma_f32_16x16x32_bf16 v[12:15], v[132:135], v[212:215], v[12:15]
	v_mfma_f32_16x16x32_bf16 v[8:11], v[148:151], v[212:215], v[8:11]
	v_lshl_add_u64 v[220:221], v[136:137], 0, s[86:87]
	s_mov_b32 m0, s82
	s_nop 0
	global_load_lds_dwordx4 v[220:221], off
	v_mfma_f32_16x16x32_bf16 v[60:63], v[144:147], v[176:179], v[60:63]
	v_mfma_f32_16x16x32_bf16 v[56:59], v[152:155], v[176:179], v[56:59]
	v_mfma_f32_16x16x32_bf16 v[44:47], v[144:147], v[200:203], v[44:47]
	v_mfma_f32_16x16x32_bf16 v[40:43], v[152:155], v[200:203], v[40:43]
	v_mfma_f32_16x16x32_bf16 v[28:31], v[144:147], v[208:211], v[28:31]
	v_mfma_f32_16x16x32_bf16 v[24:27], v[152:155], v[208:211], v[24:27]
	v_mfma_f32_16x16x32_bf16 v[12:15], v[144:147], v[216:219], v[12:15]
	v_mfma_f32_16x16x32_bf16 v[8:11], v[152:155], v[216:219], v[8:11]
	v_lshl_add_u64 v[220:221], v[136:137], 0, s[88:89]
	s_add_i32 m0, s82, 0x2000
	s_nop 0
	global_load_lds_dwordx4 v[220:221], off
	v_mfma_f32_16x16x32_bf16 v[52:55], v[156:159], v[172:175], v[52:55]
	v_mfma_f32_16x16x32_bf16 v[48:51], v[164:167], v[172:175], v[48:51]
	v_mfma_f32_16x16x32_bf16 v[36:39], v[156:159], v[180:183], v[36:39]
	v_mfma_f32_16x16x32_bf16 v[32:35], v[164:167], v[180:183], v[32:35]
	v_mfma_f32_16x16x32_bf16 v[20:23], v[156:159], v[204:207], v[20:23]
	v_mfma_f32_16x16x32_bf16 v[16:19], v[164:167], v[204:207], v[16:19]
	v_mfma_f32_16x16x32_bf16 v[4:7], v[156:159], v[212:215], v[4:7]
	v_mfma_f32_16x16x32_bf16 v[0:3], v[164:167], v[212:215], v[0:3]
	v_lshl_add_u64 v[220:221], s[2:3], 0, v[128:129]
	s_mov_b32 m0, s51
	v_lshl_add_u64 v[222:223], v[220:221], 0, s[84:85]
	global_load_lds_dwordx4 v[220:221], off
	v_mfma_f32_16x16x32_bf16 v[52:55], v[160:163], v[176:179], v[52:55]
	v_mfma_f32_16x16x32_bf16 v[48:51], v[168:171], v[176:179], v[48:51]
	v_mfma_f32_16x16x32_bf16 v[36:39], v[160:163], v[200:203], v[36:39]
	v_mfma_f32_16x16x32_bf16 v[32:35], v[168:171], v[200:203], v[32:35]
	v_mfma_f32_16x16x32_bf16 v[20:23], v[160:163], v[208:211], v[20:23]
	v_mfma_f32_16x16x32_bf16 v[16:19], v[168:171], v[208:211], v[16:19]
	s_mov_b32 m0, s66
	s_nop 0
	global_load_lds_dwordx4 v[222:223], off
	v_mfma_f32_16x16x32_bf16 v[4:7], v[160:163], v[216:219], v[4:7]
	v_mfma_f32_16x16x32_bf16 v[0:3], v[168:171], v[216:219], v[0:3]
	s_barrier
	s_add_i32 s2, 0, 0x18000
	v_add_u32_e32 v143, s2, v140
	s_add_i32 s3, 0, 0x1c000
	ds_read_b128 v[132:135], v143
	ds_read_b128 v[144:147], v143 offset:1024
	ds_read_b128 v[148:151], v143 offset:2048
	ds_read_b128 v[152:155], v143 offset:3072
	v_add_u32_e32 v143, s3, v140
	ds_read_b128 v[156:159], v143
	ds_read_b128 v[160:163], v143 offset:1024
	ds_read_b128 v[164:167], v143 offset:2048
	ds_read_b128 v[168:171], v143 offset:3072
	s_mov_b32 m0, s67
	v_lshl_add_u64 v[222:223], v[220:221], 0, s[86:87]
	ds_read_b128 v[172:175], v142 offset:32768
	ds_read_b128 v[176:179], v142 offset:33792
	ds_read_b128 v[180:183], v142 offset:34816
	ds_read_b128 v[200:203], v142 offset:35840
	ds_read_b128 v[204:207], v142 offset:36864
	ds_read_b128 v[208:211], v142 offset:37888
	ds_read_b128 v[212:215], v142 offset:38912
	ds_read_b128 v[216:219], v142 offset:39936
	global_load_lds_dwordx4 v[222:223], off
	v_lshl_add_u64 v[222:223], v[220:221], 0, s[88:89]
	s_mov_b32 m0, s76
	s_nop 0
	global_load_lds_dwordx4 v[222:223], off
	s_waitcnt vmcnt(8)
	s_waitcnt lgkmcnt(0)
	s_barrier
	s_waitcnt lgkmcnt(0)
	v_mfma_f32_16x16x32_bf16 v[124:127], v[132:135], v[172:175], v[124:127]
	v_mfma_f32_16x16x32_bf16 v[120:123], v[148:151], v[172:175], v[120:123]
	v_mfma_f32_16x16x32_bf16 v[108:111], v[132:135], v[180:183], v[108:111]
	v_mfma_f32_16x16x32_bf16 v[104:107], v[148:151], v[180:183], v[104:107]
	v_mfma_f32_16x16x32_bf16 v[92:95], v[132:135], v[204:207], v[92:95]
	v_mfma_f32_16x16x32_bf16 v[88:91], v[148:151], v[204:207], v[88:91]
	v_mfma_f32_16x16x32_bf16 v[76:79], v[132:135], v[212:215], v[76:79]
	v_mfma_f32_16x16x32_bf16 v[72:75], v[148:151], v[212:215], v[72:75]
	v_mfma_f32_16x16x32_bf16 v[124:127], v[144:147], v[176:179], v[124:127]
	v_mfma_f32_16x16x32_bf16 v[120:123], v[152:155], v[176:179], v[120:123]
	v_mfma_f32_16x16x32_bf16 v[108:111], v[144:147], v[200:203], v[108:111]
	v_mfma_f32_16x16x32_bf16 v[104:107], v[152:155], v[200:203], v[104:107]
	v_mfma_f32_16x16x32_bf16 v[92:95], v[144:147], v[208:211], v[92:95]
	v_mfma_f32_16x16x32_bf16 v[88:91], v[152:155], v[208:211], v[88:91]
	v_mfma_f32_16x16x32_bf16 v[76:79], v[144:147], v[216:219], v[76:79]
	v_mfma_f32_16x16x32_bf16 v[72:75], v[152:155], v[216:219], v[72:75]
	v_mfma_f32_16x16x32_bf16 v[116:119], v[156:159], v[172:175], v[116:119]
	v_mfma_f32_16x16x32_bf16 v[112:115], v[164:167], v[172:175], v[112:115]
	v_mfma_f32_16x16x32_bf16 v[100:103], v[156:159], v[180:183], v[100:103]
	v_mfma_f32_16x16x32_bf16 v[96:99], v[164:167], v[180:183], v[96:99]
	v_mfma_f32_16x16x32_bf16 v[84:87], v[156:159], v[204:207], v[84:87]
	v_mfma_f32_16x16x32_bf16 v[80:83], v[164:167], v[204:207], v[80:83]
	v_mfma_f32_16x16x32_bf16 v[68:71], v[156:159], v[212:215], v[68:71]
	v_mfma_f32_16x16x32_bf16 v[64:67], v[164:167], v[212:215], v[64:67]
	v_mfma_f32_16x16x32_bf16 v[116:119], v[160:163], v[176:179], v[116:119]
	v_mfma_f32_16x16x32_bf16 v[112:115], v[168:171], v[176:179], v[112:115]
	v_mfma_f32_16x16x32_bf16 v[100:103], v[160:163], v[200:203], v[100:103]
	v_mfma_f32_16x16x32_bf16 v[96:99], v[168:171], v[200:203], v[96:99]
	v_mfma_f32_16x16x32_bf16 v[84:87], v[160:163], v[208:211], v[84:87]
	v_mfma_f32_16x16x32_bf16 v[80:83], v[168:171], v[208:211], v[80:83]
	v_mfma_f32_16x16x32_bf16 v[68:71], v[160:163], v[216:219], v[68:71]
	v_mfma_f32_16x16x32_bf16 v[64:67], v[168:171], v[216:219], v[64:67]
	s_barrier
	s_add_i32 s2, s2, s50
	v_lshl_add_u64 v[222:223], v[136:137], 0, s[90:91]
	s_mov_b32 m0, s2
	ds_read_b128 v[172:175], v142 offset:49152
	ds_read_b128 v[176:179], v142 offset:50176
	ds_read_b128 v[180:183], v142 offset:51200
	ds_read_b128 v[200:203], v142 offset:52224
	ds_read_b128 v[204:207], v142 offset:53248
	ds_read_b128 v[208:211], v142 offset:54272
	ds_read_b128 v[212:215], v142 offset:55296
	ds_read_b128 v[216:219], v142 offset:56320
	global_load_lds_dwordx4 v[222:223], off
	v_lshl_add_u64 v[222:223], v[136:137], 0, s[92:93]
	s_add_i32 m0, s2, 0x2000
	s_add_i32 s2, s3, s50
	global_load_lds_dwordx4 v[222:223], off
	s_waitcnt vmcnt(4)
	s_waitcnt lgkmcnt(0)
	s_barrier
	s_waitcnt lgkmcnt(0)
	v_mfma_f32_16x16x32_bf16 v[60:63], v[132:135], v[172:175], v[60:63]
	v_mfma_f32_16x16x32_bf16 v[56:59], v[148:151], v[172:175], v[56:59]
	v_mfma_f32_16x16x32_bf16 v[44:47], v[132:135], v[180:183], v[44:47]
	v_mfma_f32_16x16x32_bf16 v[40:43], v[148:151], v[180:183], v[40:43]
	v_mfma_f32_16x16x32_bf16 v[28:31], v[132:135], v[204:207], v[28:31]
	v_mfma_f32_16x16x32_bf16 v[24:27], v[148:151], v[204:207], v[24:27]
	v_mfma_f32_16x16x32_bf16 v[12:15], v[132:135], v[212:215], v[12:15]
	v_mfma_f32_16x16x32_bf16 v[8:11], v[148:151], v[212:215], v[8:11]
	v_lshl_add_u64 v[222:223], v[136:137], 0, s[94:95]
	s_mov_b32 m0, s2
	v_lshl_add_u64 v[136:137], v[136:137], 0, s[96:97]
	global_load_lds_dwordx4 v[222:223], off
	v_mfma_f32_16x16x32_bf16 v[60:63], v[144:147], v[176:179], v[60:63]
	v_mfma_f32_16x16x32_bf16 v[56:59], v[152:155], v[176:179], v[56:59]
	v_mfma_f32_16x16x32_bf16 v[44:47], v[144:147], v[200:203], v[44:47]
	v_mfma_f32_16x16x32_bf16 v[40:43], v[152:155], v[200:203], v[40:43]
	v_mfma_f32_16x16x32_bf16 v[28:31], v[144:147], v[208:211], v[28:31]
	v_mfma_f32_16x16x32_bf16 v[24:27], v[152:155], v[208:211], v[24:27]
	v_mfma_f32_16x16x32_bf16 v[12:15], v[144:147], v[216:219], v[12:15]
	v_mfma_f32_16x16x32_bf16 v[8:11], v[152:155], v[216:219], v[8:11]
	s_add_i32 m0, s2, 0x2000
	s_nop 0
	global_load_lds_dwordx4 v[136:137], off
	v_mfma_f32_16x16x32_bf16 v[52:55], v[156:159], v[172:175], v[52:55]
	v_mfma_f32_16x16x32_bf16 v[48:51], v[164:167], v[172:175], v[48:51]
	v_mfma_f32_16x16x32_bf16 v[36:39], v[156:159], v[180:183], v[36:39]
	v_mfma_f32_16x16x32_bf16 v[32:35], v[164:167], v[180:183], v[32:35]
	v_mfma_f32_16x16x32_bf16 v[20:23], v[156:159], v[204:207], v[20:23]
	v_mfma_f32_16x16x32_bf16 v[16:19], v[164:167], v[204:207], v[16:19]
	v_mfma_f32_16x16x32_bf16 v[4:7], v[156:159], v[212:215], v[4:7]
	v_mfma_f32_16x16x32_bf16 v[0:3], v[164:167], v[212:215], v[0:3]
	v_lshl_add_u64 v[136:137], v[220:221], 0, s[90:91]
	s_mov_b32 m0, s77
	s_nop 0
	global_load_lds_dwordx4 v[136:137], off
	v_mfma_f32_16x16x32_bf16 v[52:55], v[160:163], v[176:179], v[52:55]
	v_mfma_f32_16x16x32_bf16 v[48:51], v[168:171], v[176:179], v[48:51]
	v_mfma_f32_16x16x32_bf16 v[36:39], v[160:163], v[200:203], v[36:39]
	v_mfma_f32_16x16x32_bf16 v[32:35], v[168:171], v[200:203], v[32:35]
	v_mfma_f32_16x16x32_bf16 v[20:23], v[160:163], v[208:211], v[20:23]
	v_mfma_f32_16x16x32_bf16 v[16:19], v[168:171], v[208:211], v[16:19]
	v_lshl_add_u64 v[136:137], v[220:221], 0, s[92:93]
	s_mov_b32 m0, s78
	s_nop 0
	global_load_lds_dwordx4 v[136:137], off
	v_mfma_f32_16x16x32_bf16 v[4:7], v[160:163], v[216:219], v[4:7]
	v_mfma_f32_16x16x32_bf16 v[0:3], v[168:171], v[216:219], v[0:3]
	s_barrier
	s_add_i32 s81, s81, 2
	s_add_u32 s54, s54, 0x100
	s_addc_u32 s55, s55, 0
	s_add_u32 s49, s49, 0x100
	s_addc_u32 s80, s80, 0
	s_cmp_gt_u32 s81, 13
	s_cbranch_scc0 .LBB0_1916
	s_and_b64 vcc, exec, s[18:19]
	s_cbranch_vccz .LBB0_1919
	s_barrier
